# MLA: next tile's K/V global loads issued before the tile barrier (longer latency window)
# baseline (speedup 1.0000x reference)
.LBB0_1370:
	v_exp_f32_e32 v96, v96
	v_exp_f32_e32 v97, v97
	v_exp_f32_e32 v98, v98
	v_exp_f32_e32 v99, v99
	v_exp_f32_e32 v100, v100
	v_exp_f32_e32 v101, v101
	v_exp_f32_e32 v102, v102
	v_exp_f32_e32 v103, v103
	v_cvt_pk_bf16_f32 v96, v96, v97
	v_cvt_pk_bf16_f32 v97, v98, v99
	v_cvt_pk_bf16_f32 v98, v100, v101
	v_cvt_pk_bf16_f32 v99, v102, v103
	v_exp_f32_e32 v88, v88
	v_exp_f32_e32 v89, v89
	v_exp_f32_e32 v90, v90
	v_exp_f32_e32 v91, v91
	v_exp_f32_e32 v100, v92
	v_exp_f32_e32 v101, v93
	v_exp_f32_e32 v102, v94
	v_exp_f32_e32 v103, v95
	v_mov_b64_e32 v[136:137], s[14:15]
	v_mov_b64_e32 v[134:135], s[12:13]
	v_mov_b32_e32 v109, v108
	v_mov_b32_e32 v110, v108
	v_mov_b32_e32 v111, v108
	s_waitcnt lgkmcnt(1)
	v_mov_b32_e32 v105, v104
	v_mov_b32_e32 v106, v104
	s_waitcnt lgkmcnt(0)
	v_mov_b32_e32 v107, v104
	v_cvt_pk_bf16_f32 v88, v88, v89
	v_cvt_pk_bf16_f32 v89, v90, v91
	v_cvt_pk_bf16_f32 v90, v100, v101
	v_cvt_pk_bf16_f32 v91, v102, v103
	v_mfma_f32_16x16x32_bf16 v[100:103], v[68:71], v[96:99], v[108:111]
	v_exp_f32_e32 v113, v76
	v_exp_f32_e32 v115, v81
	v_exp_f32_e32 v117, v82
	v_mfma_f32_16x16x32_bf16 v[122:125], v[68:71], v[88:91], v[104:107]
	v_exp_f32_e32 v68, v77
	v_exp_f32_e32 v69, v78
	v_exp_f32_e32 v70, v79
	v_mfma_f32_16x16x32_bf16 v[76:79], v[64:67], v[96:99], v[108:111]
	v_exp_f32_e32 v71, v80
	v_cvt_pk_bf16_f32 v80, v113, v68
	v_cvt_pk_bf16_f32 v81, v69, v70
	v_mfma_f32_16x16x32_bf16 v[126:129], v[64:67], v[88:91], v[104:107]
	v_exp_f32_e32 v64, v83
	v_cvt_pk_bf16_f32 v82, v71, v115
	s_waitcnt vmcnt(1)
	ds_write_b128 v121, v[32:35] offset:14336
	v_mfma_f32_16x16x32_bf16 v[130:133], v[52:55], v[96:99], v[108:111]
	v_cvt_pk_bf16_f32 v83, v117, v64
	v_lshlrev_b32_e32 v144, 1, v116
	v_mfma_f32_16x16x32_bf16 v[138:141], v[52:55], v[88:91], v[104:107]
	v_exp_f32_e32 v52, v56
	v_exp_f32_e32 v53, v57
	v_exp_f32_e32 v54, v58
	v_exp_f32_e32 v55, v59
	v_exp_f32_e32 v56, v60
	v_exp_f32_e32 v57, v61
	v_exp_f32_e32 v58, v62
	v_exp_f32_e32 v59, v63
	v_mfma_f32_16x16x32_bf16 v[92:95], v[84:87], v[96:99], v[108:111]
	v_mfma_f32_16x16x32_bf16 v[84:87], v[84:87], v[88:91], v[104:107]
	v_mfma_f32_16x16x32_bf16 v[96:99], v[134:137], v[96:99], v[108:111]
	v_mfma_f32_16x16x32_bf16 v[88:91], v[134:137], v[88:91], v[104:107]
	s_nop 2
	v_cvt_pk_bf16_f32 v104, v52, v53
	v_cvt_pk_bf16_f32 v105, v54, v55
	v_cvt_pk_bf16_f32 v106, v56, v57
	v_cvt_pk_bf16_f32 v107, v58, v59
	v_mfma_f32_16x16x32_bf16 v[68:71], v[48:51], v[80:83], v[92:95]
	s_nop 0
	v_mfma_f32_16x16x32_bf16 v[64:67], v[48:51], v[104:107], v[84:87]
	v_mfma_f32_16x16x32_bf16 v[60:63], v[44:47], v[80:83], v[100:103]
	v_mfma_f32_16x16x32_bf16 v[56:59], v[44:47], v[104:107], v[122:125]
	v_mfma_f32_16x16x32_bf16 v[52:55], v[40:43], v[80:83], v[76:79]
	v_mfma_f32_16x16x32_bf16 v[48:51], v[40:43], v[104:107], v[126:129]
	v_mfma_f32_16x16x32_bf16 v[44:47], v[36:39], v[80:83], v[130:133]
	v_mfma_f32_16x16x32_bf16 v[40:43], v[36:39], v[104:107], v[138:141]
	v_mfma_f32_16x16x32_bf16 v[36:39], v[134:137], v[80:83], v[96:99]
	v_mfma_f32_16x16x32_bf16 v[32:35], v[134:137], v[104:107], v[88:91]
	s_and_saveexec_b64 s[26:27], s[6:7]
	v_lshl_add_u32 v76, v171, 1, v144
	ds_write_b128 v76, v[28:31] offset:14336
	s_or_b64 exec, exec, s[26:27]
	s_lshl_b32 s26, s43, 8
	v_mov_b32_e32 v115, v145
	s_addk_i32 s26, 0x7800
	s_mov_b32 s27, 1
	v_lshl_add_u64 v[160:161], s[0:1], 0, v[114:115]
	v_add_u32_e32 v177, 0x80, v119
	v_add_u32_e32 v178, 0x80, v120
	v_add_u32_e32 v179, 0x80, v118
	v_lshlrev_b32_e32 v180, 1, v112
	v_mov_b32_e32 v203, 0
	v_mov_b32_e32 v210, v179
	v_mov_b32_e32 v211, 0
	v_mov_b32_e32 v214, 0x800
	v_lshlrev_b64 v[212:213], 11, v[210:211]
	v_lshlrev_b64 v[210:211], 6, v[210:211]
	v_lshl_add_u64 v[210:211], v[152:153], 0, v[210:211]
	v_lshl_add_u64 v[212:213], v[150:151], 0, v[212:213]
	v_lshl_add_u64 v[210:211], v[210:211], 0, s[24:25]
	v_cndmask_b32_e64 v205, v211, v213, s[4:5]
	v_cndmask_b32_e64 v204, v210, v212, s[4:5]
	v_mov_b32_e32 v206, 64
	v_cndmask_b32_e64 v206, v206, v214, s[4:5]
	v_mov_b32_e32 v210, v177
	v_mov_b32_e32 v211, 0
	v_lshlrev_b64 v[212:213], 11, v[210:211]
	v_lshlrev_b64 v[210:211], 6, v[210:211]
	v_lshl_add_u64 v[212:213], v[156:157], 0, v[212:213]
	v_lshl_add_u64 v[210:211], v[154:155], 0, v[210:211]
	v_cndmask_b32_e64 v209, v211, v213, s[8:9]
	v_cndmask_b32_e64 v208, v210, v212, s[8:9]
	v_mov_b32_e32 v207, 64
	v_cndmask_b32_e64 v207, v207, v214, s[8:9]
	v_mov_b32_e32 v210, v178
	v_mov_b32_e32 v211, 0
	v_lshlrev_b64 v[210:211], 11, v[210:211]
	v_lshl_add_u64 v[216:217], v[160:161], 0, v[210:211]
	v_xor_b32_e32 v218, 0x80000000, v159
	v_xor_b32_e32 v222, 0x80000000, v158
	v_mov_b32_e32 v219, v218
	v_mov_b32_e32 v220, v218
	v_mov_b32_e32 v221, v218
	v_mov_b32_e32 v223, v222
	v_mov_b32_e32 v224, v222
	v_mov_b32_e32 v225, v222
	v_mov_b64_e32 v[228:229], s[12:13]
	v_mov_b64_e32 v[230:231], s[14:15]
	s_waitcnt vmcnt(0)
	ds_write_b128 v174, v[72:75] offset:38912
	s_branch .Lmla_ld
.LBB0_1373:
	s_or_b64 exec, exec, s[0:1]
	s_add_i32 s27, s27, 1
	s_mulk_i32 s43, 0x2800
	v_add_u32_e32 v72, s43, v174
	s_cmp_lg_u32 s27, 35
	s_waitcnt vmcnt(0)
	ds_write_b128 v72, v[232:235] offset:28672
	s_cbranch_scc0 .Lmla_nold

.Lmla_nold:
	s_waitcnt lgkmcnt(0)
	s_barrier
	s_cmp_lg_u32 s27, 35
	s_cbranch_scc0 .LBB0_1380
.LBB0_1374:
	s_and_b32 s99, s27, 1
	s_mul_i32 s99, s99, 0x3800
	v_add_u32_e32 v124, s99, v175
	ds_read_b128 v[76:79], v124
	ds_read_b128 v[88:91], v124 offset:64
	s_and_b32 s0, s27, 1
	s_mul_i32 s1, s0, 0x3800
	s_waitcnt lgkmcnt(1)
	v_mfma_f32_16x16x32_bf16 v[92:95], v[76:79], v[20:23], v[218:221]
	ds_read_b128 v[96:99], v124 offset:3584
	ds_read_b128 v[100:103], v124 offset:128
	ds_read_b128 v[108:111], v124 offset:7168
	ds_read_b128 v[112:115], v124 offset:7232
	ds_read_b128 v[120:123], v124 offset:10752
	ds_read_b128 v[182:185], v124 offset:7296
	v_mfma_f32_16x16x32_bf16 v[76:79], v[76:79], v[24:27], v[222:225]
	s_mul_i32 s1, s0, 0x2800
	s_waitcnt lgkmcnt(5)
	v_mfma_f32_16x16x32_bf16 v[104:107], v[96:99], v[20:23], v[218:221]
	v_mfma_f32_16x16x32_bf16 v[96:99], v[96:99], v[24:27], v[222:225]
	s_waitcnt lgkmcnt(3)
	v_mfma_f32_16x16x32_bf16 v[116:119], v[108:111], v[20:23], v[218:221]
	v_mfma_f32_16x16x32_bf16 v[108:111], v[108:111], v[24:27], v[222:225]
	s_waitcnt lgkmcnt(1)
	v_mfma_f32_16x16x32_bf16 v[80:83], v[120:123], v[20:23], v[218:221]
	v_mfma_f32_16x16x32_bf16 v[84:87], v[120:123], v[24:27], v[222:225]
	v_mfma_f32_16x16x32_bf16 v[92:95], v[88:91], v[12:15], v[92:95]
	v_mfma_f32_16x16x32_bf16 v[76:79], v[88:91], v[16:19], v[76:79]
	ds_read_b128 v[88:91], v124 offset:3648
	ds_read_b128 v[120:123], v124 offset:3712
	s_waitcnt lgkmcnt(1)
	v_mfma_f32_16x16x32_bf16 v[104:107], v[88:91], v[12:15], v[104:107]
	v_mfma_f32_16x16x32_bf16 v[88:91], v[88:91], v[16:19], v[96:99]
	s_nop 2
	ds_read_b128 v[96:99], v124 offset:10816
	ds_read_b128 v[190:193], v124 offset:10880
	s_waitcnt lgkmcnt(1)
	v_mfma_f32_16x16x32_bf16 v[194:197], v[96:99], v[12:15], v[80:83]
	s_nop 2
	v_mfma_f32_16x16x32_bf16 v[128:131], v[100:103], v[4:7], v[76:79]
	v_add_u32_e32 v82, s1, v176
	s_nop 1
	v_mfma_f32_16x16x32_bf16 v[116:119], v[112:115], v[12:15], v[116:119]
	v_mfma_f32_16x16x32_bf16 v[186:189], v[112:115], v[16:19], v[108:111]
	v_mfma_f32_16x16x32_bf16 v[198:201], v[96:99], v[16:19], v[84:87]
	ds_read_b64_tr_b16 v[124:125], v82 offset:28672
	ds_read_b64_tr_b16 v[112:113], v82 offset:28704
	ds_read_b64_tr_b16 v[108:109], v82 offset:28736
	ds_read_b64_tr_b16 v[96:97], v82 offset:28768
	ds_read_b64_tr_b16 v[126:127], v82 offset:31232
	ds_read_b64_tr_b16 v[114:115], v82 offset:31264
	ds_read_b64_tr_b16 v[110:111], v82 offset:31296
	ds_read_b64_tr_b16 v[98:99], v82 offset:31328
	v_mfma_f32_16x16x32_bf16 v[136:139], v[100:103], v[8:11], v[92:95]
	v_mfma_f32_16x16x32_bf16 v[132:135], v[120:123], v[4:7], v[88:91]
	s_nop 1
	ds_read_b64_tr_b16 v[92:93], v82 offset:33792
	ds_read_b64_tr_b16 v[88:89], v82 offset:33824
	ds_read_b64_tr_b16 v[84:85], v82 offset:33856
	ds_read_b64_tr_b16 v[80:81], v82 offset:33888
	ds_read_b64_tr_b16 v[94:95], v82 offset:36352
	ds_read_b64_tr_b16 v[90:91], v82 offset:36384
	ds_read_b64_tr_b16 v[86:87], v82 offset:36416
	ds_read_b64_tr_b16 v[82:83], v82 offset:36448
	v_mfma_f32_16x16x32_bf16 v[140:143], v[120:123], v[8:11], v[104:107]
	v_mfma_f32_16x16x32_bf16 v[116:119], v[182:185], v[8:11], v[116:119]
	v_mfma_f32_16x16x32_bf16 v[100:103], v[182:185], v[4:7], v[186:189]
	s_waitcnt lgkmcnt(14)
	v_mfma_f32_16x16x32_bf16 v[120:123], v[190:193], v[8:11], v[194:197]
	v_mfma_f32_16x16x32_bf16 v[104:107], v[190:193], v[4:7], v[198:201]
	v_max3_f32 v181, v136, v137, v138
	v_max3_f32 v183, v128, v129, v130
	v_max3_f32 v184, v131, v132, v133
	v_max3_f32 v181, v181, v139, v140
	v_max3_f32 v183, v183, v134, v135
	v_max3_f32 v181, v181, v141, v142
	v_max3_f32 v182, v143, v116, v117
	v_max3_f32 v184, v184, v100, v101
	v_max3_f32 v182, v182, v118, v119
	v_max3_f32 v184, v184, v102, v103
	v_max3_f32 v181, v181, v120, v121
	v_max3_f32 v182, v182, v122, v123
	v_max3_f32 v183, v183, v104, v105
	v_max3_f32 v184, v184, v106, v107
	v_max_f32_e32 v181, v181, v182
	v_max_f32_e32 v183, v183, v184
	v_max_f32_e32 v184, v181, v183
	v_cmp_lt_f32_e32 vcc, s36, v184
	s_cbranch_vccz .LBB0_1378
	v_mov_b32_e32 v182, v181
	v_mov_b32_e32 v184, v183
	s_nop 1
	v_permlane16_swap_b32_e32 v181, v182
	v_permlane16_swap_b32_e32 v183, v184
	v_max_f32_e32 v181, v181, v182
	v_max_f32_e32 v183, v183, v184
	v_mov_b32_e32 v182, v181
	v_mov_b32_e32 v184, v183
	s_nop 1
	v_permlane32_swap_b32_e32 v181, v182
	v_permlane32_swap_b32_e32 v183, v184
	v_max_f32_e32 v182, v181, v182
	v_max_f32_e32 v181, v183, v184
	v_max_f32_e32 v182, v182, v182
	v_max_f32_e32 v183, 0, v182
	v_exp_f32_e64 v182, -v183
	v_max_f32_e32 v181, v181, v181
	v_sub_f32_e32 v136, v136, v183
	v_sub_f32_e32 v137, v137, v183
	v_pk_mul_f32 v[70:71], v[70:71], v[182:183] op_sel_hi:[1,0]
	v_pk_mul_f32 v[68:69], v[68:69], v[182:183] op_sel_hi:[1,0]
	v_pk_mul_f32 v[62:63], v[62:63], v[182:183] op_sel_hi:[1,0]
	v_pk_mul_f32 v[60:61], v[60:61], v[182:183] op_sel_hi:[1,0]
	v_pk_mul_f32 v[54:55], v[54:55], v[182:183] op_sel_hi:[1,0]
	v_pk_mul_f32 v[52:53], v[52:53], v[182:183] op_sel_hi:[1,0]
	v_pk_mul_f32 v[46:47], v[46:47], v[182:183] op_sel_hi:[1,0]
	v_pk_mul_f32 v[44:45], v[44:45], v[182:183] op_sel_hi:[1,0]
	v_pk_mul_f32 v[38:39], v[38:39], v[182:183] op_sel_hi:[1,0]
	v_pk_mul_f32 v[36:37], v[36:37], v[182:183] op_sel_hi:[1,0]
	v_max_f32_e32 v182, 0, v181
	v_exp_f32_e64 v184, -v182
	v_sub_f32_e32 v138, v138, v183
	v_sub_f32_e32 v139, v139, v183
	v_sub_f32_e32 v140, v140, v183
	v_sub_f32_e32 v141, v141, v183
	v_sub_f32_e32 v142, v142, v183
	v_sub_f32_e32 v143, v143, v183
	v_sub_f32_e32 v116, v116, v183
	v_sub_f32_e32 v117, v117, v183
	v_sub_f32_e32 v118, v118, v183
	v_sub_f32_e32 v119, v119, v183
	v_sub_f32_e32 v120, v120, v183
	v_sub_f32_e32 v121, v121, v183
	v_sub_f32_e32 v122, v122, v183
	v_sub_f32_e32 v123, v123, v183
	v_pk_add_f32 v[158:159], v[158:159], v[182:183]
	v_xor_b32_e32 v218, 0x80000000, v159
	v_xor_b32_e32 v222, 0x80000000, v158
	v_mov_b32_e32 v219, v218
	v_mov_b32_e32 v220, v218
	v_mov_b32_e32 v221, v218
	v_mov_b32_e32 v223, v222
	v_mov_b32_e32 v224, v222
	v_mov_b32_e32 v225, v222
	v_sub_f32_e32 v128, v128, v182
	v_sub_f32_e32 v129, v129, v182
	v_sub_f32_e32 v130, v130, v182
	v_sub_f32_e32 v131, v131, v182
	v_sub_f32_e32 v132, v132, v182
	v_sub_f32_e32 v133, v133, v182
	v_sub_f32_e32 v134, v134, v182
	v_sub_f32_e32 v135, v135, v182
	v_sub_f32_e32 v100, v100, v182
	v_sub_f32_e32 v101, v101, v182
	v_sub_f32_e32 v102, v102, v182
	v_sub_f32_e32 v103, v103, v182
	v_sub_f32_e32 v104, v104, v182
	v_sub_f32_e32 v105, v105, v182
	v_sub_f32_e32 v106, v106, v182
	v_sub_f32_e32 v107, v107, v182
	v_pk_mul_f32 v[66:67], v[66:67], v[184:185] op_sel_hi:[1,0]
	v_pk_mul_f32 v[64:65], v[64:65], v[184:185] op_sel_hi:[1,0]
	v_pk_mul_f32 v[58:59], v[58:59], v[184:185] op_sel_hi:[1,0]
	v_pk_mul_f32 v[56:57], v[56:57], v[184:185] op_sel_hi:[1,0]
	v_pk_mul_f32 v[50:51], v[50:51], v[184:185] op_sel_hi:[1,0]
	v_pk_mul_f32 v[48:49], v[48:49], v[184:185] op_sel_hi:[1,0]
	v_pk_mul_f32 v[42:43], v[42:43], v[184:185] op_sel_hi:[1,0]
	v_pk_mul_f32 v[40:41], v[40:41], v[184:185] op_sel_hi:[1,0]
	v_pk_mul_f32 v[34:35], v[34:35], v[184:185] op_sel_hi:[1,0]
	v_pk_mul_f32 v[32:33], v[32:33], v[184:185] op_sel_hi:[1,0]
